# layer-1 FFN1-down weight conversion moved from the P0 prologue into the idle tail of layer 0's in-projection GEMM (second pass through the tail conversion block)
# speedup vs baseline: 1.0015x; 1.0015x over previous
; #define LAS __attribute__((address_space(3)))
; __device__ __forceinline__ LAS unsigned char* lds_base() { extern __shared__ __attribute__((aligned(16))) unsigned char lds_any_[]; return (LAS unsigned char*)lds_any_; }
; __global__ void __launch_bounds__(512, 2) fwd_megakernel(Args args) {
;     ...
;     { volatile LAS unsigned* bst = (volatile LAS unsigned*)(lds_base() + (LDS_BYTES - 64));
;       if (threadIdx.x < 2) bst[threadIdx.x] = 0u;
;       if (bx == 0) { unsigned* barw = (unsigned*)(args.ws + WS_BAR); for (int i = threadIdx.x; i < BARW_TOTAL; i += 512) barw[i] = 0u; } }
_Z14fwd_megakernel4Args:
	s_load_dwordx2 s[72:73], s[0:1], 0xe8
	s_add_u32 s28, s0, 0xe8
	v_and_b32_e32 v202, 0x3ff, v0
	s_mov_b32 s58, s2
	s_addc_u32 s29, s1, 0
	v_cmp_gt_u32_e32 vcc, 2, v202
	s_and_saveexec_b64 s[4:5], vcc
	v_lshl_add_u32 v1, v202, 2, 0
	v_add_u32_e32 v1, 0x23fc0, v1
	v_mov_b32_e32 v2, 0
	ds_write_b32 v1, v2
	s_or_b64 exec, exec, s[4:5]
	s_mov_b32 s4, 0
	v_writelane_b32 v255, s4, 62
	s_load_dwordx2 s[56:57], s[0:1], 0xe0
	s_cmp_lg_u32 s58, 0
	s_mov_b32 s45, 0
	s_cbranch_scc1 .LBB0_9
	v_lshrrev_b32_e32 v1, 9, v202
	v_sub_u32_e32 v6, 16, v1
	s_waitcnt lgkmcnt(0)
	s_add_u32 s4, s56, 0x277b6800
	v_and_b32_e32 v1, 30, v6
	v_add_u32_e32 v203, 0x200, v202
	s_addc_u32 s5, s57, 0
	s_mov_b64 s[6:7], 0
	v_mov_b32_e32 v3, 0
	v_mov_b32_e32 v7, v1
	v_mov_b64_e32 v[4:5], v[202:203]

; #define LAS __attribute__((address_space(3)))
; #define OPQ_V(x) asm volatile("" : "+v"(x))
; __device__ __forceinline__ void p0_item(const float* s0, const float* s1, int nv0, int nv1, int N, bf16* dst, int K, LAS float* scr, int lane, const float* gain  ) {
;     const int r = lane >> 4, c4 = lane & 15, hf = c4 >> 3, cc = (c4 & 7) * 4;
;     const float* src = (hf ? s1 : s0) + (size_t)r * N + cc;
;     const bool ok = cc < (hf ? nv1 : nv0);
;     f32x4 v[16];
; #pragma unroll
;     for (int i = 0; i < 16; ++i) v[i] = ok ? __builtin_nontemporal_load((const f32x4*)(src + (size_t)(4 * i) * N)) : (f32x4){0.f, 0.f, 0.f, 0.f};
; #pragma unroll
;     for (int i = 0; i < 16; ++i) { const float gk = gain ? gain[4 * i + r] : 1.f; LAS float* d = scr + (4 * i + r) * 65 + 4 * c4; d[0] = v[i].x * gk; d[1] = v[i].y * gk; d[2] = v[i].z * gk; d[3] = v[i].w * gk; }
;     const int c = lane & 7;
; #pragma unroll
;     for (int j = 0; j < 8; ++j) {
;         const int n = (lane >> 3) + 8 * j; const LAS float* s = scr + (8 * c) * 65 + n;
; __global__ void __launch_bounds__(512, 2) fwd_megakernel(Args args) {
;     ...
;     {
;         unsigned char* ws = args.ws;
;         int tid_ = threadIdx.x; OPQ_V(tid_); const int tid = tid_, lane = tid & 63, wave = __builtin_amdgcn_readfirstlane(tid >> 6);
;         const int gw = bx * 8 + wave, NGW = G * 8;
;         LAS float* scr = (LAS float*)((LAS unsigned char*)lds + wave * 16640);
; #pragma unroll 1
;         for (int l = 0; l < NLAYER; ++l) {
;             unsigned char* lw = ws + (size_t)l * LW_BYTES;
;             conv_set(CV_ARGS(args), ws, l, l == 0 ? (CV_GU1 | CV_D1 | CV_WIN) : CV_D1, scr, gw, NGW, lane);
.LBB0_9:
	v_mov_b32_e32 v1, v202
	s_lshl_b32 s4, s58, 3
	v_readfirstlane_b32 s2, v1
	s_ashr_i32 s3, s2, 6
	s_add_i32 s30, s3, s4
	s_mul_i32 s4, s3, 0x4100
	v_lshlrev_b32_e32 v3, 4, v1
	s_add_i32 s6, s4, 0
	v_and_b32_e32 v3, 0xf0, v3
	v_bfe_u32 v70, v1, 4, 2
	v_add_u32_e32 v67, s6, v3
	s_movk_i32 s8, 0x104
	v_mov_b32_e32 v3, 0x410
	v_mad_u32_u24 v71, v70, s8, v3
	v_mov_b32_e32 v3, 0x820
	v_mad_u32_u24 v113, v70, s8, v3
	v_mov_b32_e32 v3, 0xc30
	s_load_dwordx16 s[12:27], s[0:1], 0x8
	v_mad_u32_u24 v118, v70, s8, v3
	v_mov_b32_e32 v3, 0x1040
	s_waitcnt lgkmcnt(0)
	v_writelane_b32 v255, s20, 58
	v_writelane_b32 v255, s21, 59
	s_lshl_b32 s34, s72, 3
	v_mad_u32_u24 v119, v70, s8, v3
	v_mov_b32_e32 v3, 0x1450
	s_cmpk_lt_i32 s30, 0xac0
	v_mad_u32_u24 v120, v70, s8, v3
	v_mov_b32_e32 v3, 0x1860
	s_cselect_b64 s[46:47], -1, 0
	s_lshl_b32 s59, s58, 9
	v_mad_u32_u24 v121, v70, s8, v3
	v_mov_b32_e32 v3, 0x1c70
	s_cmpk_lt_i32 s30, 0x1580
	v_mad_u32_u24 v122, v70, s8, v3
	v_mov_b32_e32 v3, 0x2080
	s_cselect_b64 s[48:49], -1, 0
	s_cmp_lg_u64 s[14:15], 0
	v_mad_u32_u24 v123, v70, s8, v3
	v_mov_b32_e32 v3, 0x2490
	s_cselect_b64 s[50:51], -1, 0
	v_mad_u32_u24 v124, v70, s8, v3
	v_mov_b32_e32 v3, 0x28a0
	v_lshlrev_b32_e32 v4, 3, v1
	s_cmpk_lt_i32 s30, 0x1180
	v_mad_u32_u24 v125, v70, s8, v3
	v_bfe_u32 v3, v1, 3, 3
	v_and_b32_e32 v4, 56, v4
	s_cselect_b64 s[52:53], -1, 0
	s_cmp_lg_u64 s[22:23], 0
	s_load_dwordx8 s[36:43], s[0:1], 0x80
	v_add_u32_e32 v68, s59, v1
	v_mul_u32_u24_e32 v5, 0x104, v4
	v_lshlrev_b32_e32 v6, 2, v3
	s_cselect_b64 s[54:55], -1, 0
	s_lshl_b32 s35, s58, 8
	s_lshl_b32 s3, s3, 5
	s_movk_i32 s7, 0x1580
	v_add3_u32 v126, s6, v5, v6
	v_mov_b32_e32 v5, 0x2b000
	s_add_i32 s35, s35, s3
	s_lshl_b32 s3, s72, 8
	s_andn2_b32 s2, s2, 63
	v_ashrrev_i32_e32 v69, 31, v68
	v_mad_u32_u24 v24, v3, s7, v5
	v_mov_b32_e32 v5, 0x35c00
	v_writelane_b32 v253, s3, 0
	s_add_i32 s59, s59, s2
	v_lshl_add_u64 v[32:33], v[68:69], 1, s[56:57]
	s_mov_b64 s[2:3], 0xb610000
	v_mad_u32_u24 v26, v3, s7, v5
	v_mov_b32_e32 v5, 0x40800
	v_lshl_add_u64 v[74:75], v[32:33], 0, s[2:3]
	v_lshlrev_b64 v[32:33], 2, v[68:69]
	v_and_b32_e32 v69, 63, v1
	v_mul_u32_u24_e32 v2, 0x1580, v70
	v_lshlrev_b32_e32 v6, 11, v3
	v_mad_u32_u24 v28, v3, s7, v5
	v_mov_b32_e32 v5, 0x4b400
	s_lshl_b32 s76, s72, 9
	v_lshlrev_b32_e32 v66, 2, v69
	s_mov_b32 s31, 0x20000
	s_movk_i32 s4, 0x2700
	v_or_b32_e32 v8, 0x4000, v6
	v_or_b32_e32 v10, 0x8000, v6
	v_or_b32_e32 v12, 0xc000, v6
	v_or_b32_e32 v14, 0x10000, v6
	v_or_b32_e32 v16, 0x14000, v6
	v_or_b32_e32 v18, 0x18000, v6
	v_or_b32_e32 v20, 0x1c000, v6
	v_lshlrev_b32_e32 v22, 11, v70
	v_mad_u32_u24 v30, v3, s7, v5
	v_and_b32_e32 v127, 15, v1
	s_ashr_i32 s77, s76, 31
	s_waitcnt lgkmcnt(0)
	v_lshl_add_u64 v[76:77], s[40:41], 0, v[32:33]
	v_writelane_b32 v253, s56, 1
	s_mov_b64 s[2:3], 0xb650800
	v_lshlrev_b32_e32 v72, 2, v2
	v_lshl_add_u64 v[32:33], s[56:57], 0, v[32:33]
	v_lshlrev_b32_e32 v80, 1, v4
	v_mul_u32_u24_e32 v2, 0x2230, v70
	v_mul_u32_u24_e32 v4, 0x1580, v3
	v_and_b32_e32 v112, 28, v66
	s_movk_i32 s60, 0xac00
	s_movk_i32 s62, 0xcc00
	s_movk_i32 s64, 0xdc00
	s_movk_i32 s66, 0xec00
	s_movk_i32 s68, 0xfc00
	s_movk_i32 s70, 0xff00
	v_cmp_gt_i32_e64 s[10:11], s31, v68
	v_cmp_gt_i32_e64 s[4:5], s4, v68
	v_mov_b32_e32 v73, 0
	s_mov_b32 s33, 0x2b000
	v_lshl_add_u32 v128, v127, 4, s6
	v_writelane_b32 v253, s57, 2
	v_lshl_add_u64 v[78:79], v[32:33], 0, s[2:3]
	s_mov_b32 s84, 0x15000
	s_mov_b32 s85, 0x40000
	v_lshlrev_b32_e32 v82, 1, v6
	v_lshlrev_b32_e32 v84, 1, v8
	v_lshlrev_b32_e32 v86, 1, v10
	v_lshlrev_b32_e32 v88, 1, v12
	v_lshlrev_b32_e32 v90, 1, v14
	v_lshlrev_b32_e32 v92, 1, v16
	v_lshlrev_b32_e32 v94, 1, v18
	v_lshlrev_b32_e32 v96, 1, v20
	v_lshlrev_b32_e32 v98, 2, v22
	v_cndmask_b32_e64 v129, 0, 1, s[50:51]
	v_lshlrev_b32_e32 v100, 1, v4
	v_lshlrev_b32_e32 v102, 1, v24
	v_lshlrev_b32_e32 v104, 1, v26
	v_lshlrev_b32_e32 v106, 1, v28
	v_lshlrev_b32_e32 v108, 1, v30
	v_lshlrev_b32_e32 v110, 2, v2
	v_lshlrev_b32_e32 v114, 2, v112
	v_mul_u32_u24_e32 v130, 0x104, v70
	v_and_b32_e32 v131, 32, v66
	v_and_b32_e32 v132, 0x7f, v1
	s_mov_b32 s44, s45
	s_mov_b64 s[80:81], 0
	v_cmp_gt_u32_e64 s[6:7], 8, v127
	s_lshl_b64 s[40:41], s[76:77], 1
	s_lshl_b64 s[56:57], s[76:77], 2
	s_mov_b64 s[74:75], -1
	s_mov_b32 s61, -1
	s_mov_b32 s63, -1
	s_mov_b32 s65, -1
	s_mov_b32 s67, -1
	s_mov_b32 s69, -1
	s_mov_b32 s71, -1
	s_branch .LBB0_11

; #define LAS __attribute__((address_space(3)))
; __device__ __forceinline__ void p0_matrix(int type  , const float* W0, const float* W1, int K, int Nsrc, int Ndst, bf16* dst, LAS float* scr, int gw, int NGW, int lane, const float* gain) {
;     const int nruns = Ndst >> 6, nitems = (K >> 6) * nruns;
;     for (int it = gw; it < nitems; it += NGW) {
;         const int kb = it / nruns, nb = it - kb * nruns, n0 = nb * 64, k0 = kb * 64;
; __device__ __forceinline__ void conv_set(const CvPtrs args, unsigned char* ws, int l, unsigned mask, LAS float* scr, int gw, int NGW, int lane) {
;     ...
;     if (mask & CV_GU1) p0_matrix(1, args.in[3] + (size_t)l * D * FF, args.in[4] + (size_t)l * D * FF, D, FF, 2 * FF, (bf16*)(lw + LW_GU1), scr, gw, NGW, lane, args.in[2] + (size_t)l * D);
;     if (mask & CV_D1) p0_matrix(0, args.in[5] + (size_t)l * FF * D, nullptr, FF, D, D, (bf16*)(lw + LW_D1), scr, gw, NGW, lane, nullptr);
.LBB0_47:
	s_cmp_eq_u32 s44, 1
	s_cbranch_scc1 .LBB0_50
	s_andn2_b64 vcc, exec, s[46:47]
	s_cbranch_vccnz .LBB0_50
	s_mul_i32 s2, s44, 0x2b00000
	s_add_u32 s80, s20, s2
	s_addc_u32 s81, s21, 0
	s_add_u32 s82, s77, 0x2b00000
	s_addc_u32 s83, s90, 0
	s_mov_b32 s86, s59
	s_mov_b32 s87, s30
	s_cmpk_lg_i32 s34, 0x800
	s_cbranch_scc1 .Lrot_d1_skip
	s_mul_i32 s2, s44, 0x3c0
	s_add_i32 s87, s30, s2
	s_addk_i32 s87, 0x80
	s_and_b32 s87, s87, 0x7ff
	s_lshl_b32 s86, s87, 6

; #define LAS __attribute__((address_space(3)))
; __device__ __forceinline__ void p0_item(const float* s0, const float* s1, int nv0, int nv1, int N, bf16* dst, int K, LAS float* scr, int lane, const float* gain  ) {
;     const int r = lane >> 4, c4 = lane & 15, hf = c4 >> 3, cc = (c4 & 7) * 4;
;     const float* src = (hf ? s1 : s0) + (size_t)r * N + cc;
;     const bool ok = cc < (hf ? nv1 : nv0);
;     f32x4 v[16];
; #pragma unroll
;     for (int i = 0; i < 16; ++i) v[i] = ok ? __builtin_nontemporal_load((const f32x4*)(src + (size_t)(4 * i) * N)) : (f32x4){0.f, 0.f, 0.f, 0.f};
; #pragma unroll
;     for (int i = 0; i < 16; ++i) { const float gk = gain ? gain[4 * i + r] : 1.f; LAS float* d = scr + (4 * i + r) * 65 + 4 * c4; d[0] = v[i].x * gk; d[1] = v[i].y * gk; d[2] = v[i].z * gk; d[3] = v[i].w * gk; }
; __device__ __forceinline__ void p0_matrix(int type  , const float* W0, const float* W1, int K, int Nsrc, int Ndst, bf16* dst, LAS float* scr, int gw, int NGW, int lane, const float* gain) {
;     const int nruns = Ndst >> 6, nitems = (K >> 6) * nruns;
;     for (int it = gw; it < nitems; it += NGW) {
;         const int kb = it / nruns, nb = it - kb * nruns, n0 = nb * 64, k0 = kb * 64;
;         const float* src = W0; int c0 = n0, c1 = n0 + 32, nv0 = 32, nv1 = 32;
;         if (type == 1) { const int tile = n0 >> 8, r = n0 & 255; src = r < 128 ? W0 : W1; c0 = tile * 128 + (r & 127); c1 = c0 + 32; }
;         else if (type == 2) { c0 = win_src_col(n0, nv0); c1 = win_src_col(n0 + 32, nv1); }
;         const float* rowp = src + (size_t)k0 * Nsrc;
;         p0_item(rowp + c0, rowp + c1, nv0, nv1, Nsrc, dst + (size_t)n0 * K + k0, K, scr, lane, gain ? gain + k0 : nullptr);
.LBB0_1602:
	s_bitcmp0_b32 s19, 7
	s_mov_b32 s25, 0x15000
	s_cbranch_scc1 .LBB0_1606
	s_cmpk_gt_i32 s3, 0xabf
	s_cbranch_scc1 .LBB0_1606
	v_lshlrev_b32_e32 v4, 4, v90
	s_mul_i32 s0, s20, 0x2b00000
	v_and_b32_e32 v4, 0xf0, v4
	s_add_u32 s2, s52, s0
	v_add_u32_e32 v7, s22, v4
	v_lshlrev_b32_e32 v4, 3, v90
	s_addc_u32 s6, s53, 0
	v_lshrrev_b32_e32 v9, 3, v90
	v_and_b32_e32 v4, 56, v4
	s_add_u32 s7, s4, 0x9e80000
	v_lshrrev_b32_e32 v3, 4, v90
	v_lshlrev_b32_e32 v5, 2, v90
	v_mul_u32_u24_e32 v6, 0x104, v4
	v_lshlrev_b32_e32 v8, 2, v9
	s_movk_i32 s0, 0x1580
	v_mov_b32_e32 v10, 0x35c00
	s_addc_u32 s10, s5, 0
	v_and_b32_e32 v2, 28, v5
	v_lshlrev_b32_e32 v0, 11, v3
	v_mul_u32_u24_e32 v3, 0x104, v3
	v_add3_u32 v76, s22, v6, v8
	v_mul_u32_u24_e32 v6, 0x1580, v9
	v_mad_u32_u24 v8, v9, s0, v252
	v_mad_u32_u24 v10, v9, s0, v10
	v_mad_u32_u24 v12, v9, s0, v236
	v_mad_u32_u24 v14, v9, s0, v237
	s_lshl_b32 s0, s21, 9
	v_and_b32_e32 v77, 32, v5
	s_lshl_b32 s11, s3, 6
	s_sub_i32 s12, s76, s0
	v_lshlrev_b32_e32 v0, 2, v0
	v_lshlrev_b32_e32 v62, 2, v2
	v_add_u32_e32 v78, v7, v3
	v_lshlrev_b32_e32 v64, 1, v4
	v_lshlrev_b32_e32 v66, 1, v6
	v_lshlrev_b32_e32 v68, 1, v8
	v_lshlrev_b32_e32 v70, 1, v10
	v_lshlrev_b32_e32 v72, 1, v12
	v_lshlrev_b32_e32 v74, 1, v14
	s_mov_b32 s13, s3
	s_mov_b32 s26, 0x2b000
	s_mov_b32 s27, 0x48000
	s_mov_b32 s28, 0x50000
	s_mov_b32 s36, 0x58000
	s_mov_b32 s37, 0x60000
	s_mov_b32 s64, 0x68000
	s_mov_b32 s65, 0x70000
	s_mov_b32 s66, 0x78000
	v_readlane_b32 s0, v255, 62
	s_nop 3
	s_cmp_lg_u32 s0, 1
	s_cbranch_scc1 .Ld1ovr_skip
	v_readlane_b32 s2, v255, 58
	v_readlane_b32 s6, v255, 59
	s_nop 3
	s_mul_i32 s0, s20, 0x2b00000
	s_add_u32 s2, s2, s0
	s_addc_u32 s6, s6, 0
	s_add_u32 s7, s4, 0x2b00000
	s_addc_u32 s10, s5, 0
.Ld1ovr_skip:
.LBB0_1605:
	s_ashr_i32 s0, s13, 31
	s_lshr_b32 s0, s0, 27
	s_add_i32 s0, s13, s0
	s_ashr_i32 s0, s0, 5
	s_lshl_b32 s1, s0, 11
	s_lshl_b32 s0, s0, 6
	s_sub_i32 s16, s11, s1
	s_ashr_i32 s1, s0, 31
	s_lshl_b64 s[14:15], s[0:1], 13
	s_add_u32 s14, s2, s14
	v_add_u32_e32 v2, s16, v77
	s_addc_u32 s15, s6, s15
	v_ashrrev_i32_e32 v3, 31, v2
	v_lshl_add_u64 v[2:3], v[2:3], 2, s[14:15]
	v_lshl_add_u64 v[2:3], v[2:3], 0, v[0:1]
	v_mov_b32_e32 v63, v1
	v_lshl_add_u64 v[2:3], v[2:3], 0, v[62:63]
	v_add_co_u32_e32 v4, vcc, s69, v2
	global_load_dwordx4 v[80:83], v[2:3], off nt
	s_nop 0
	v_addc_co_u32_e32 v5, vcc, 0, v3, vcc
	global_load_dwordx4 v[58:61], v[4:5], off nt
	v_add_co_u32_e32 v4, vcc, s73, v2
	v_add_u32_e32 v63, 0x410, v78
	s_nop 0
	v_addc_co_u32_e32 v5, vcc, 0, v3, vcc
	global_load_dwordx4 v[54:57], v[4:5], off nt
	v_add_co_u32_e32 v4, vcc, s67, v2
	s_mul_i32 s23, s16, 0x2b00
	s_nop 0
	v_addc_co_u32_e32 v5, vcc, 0, v3, vcc
	global_load_dwordx4 v[50:53], v[4:5], off nt
	v_add_co_u32_e32 v4, vcc, s96, v2
	s_mul_hi_i32 s17, s16, 0x2b00
	s_nop 0
	v_addc_co_u32_e32 v5, vcc, 0, v3, vcc
	global_load_dwordx4 v[46:49], v[4:5], off nt
	v_add_co_u32_e32 v4, vcc, s85, v2
	s_add_u32 s23, s7, s23
	s_nop 0
	v_addc_co_u32_e32 v5, vcc, 0, v3, vcc
	global_load_dwordx4 v[42:45], v[4:5], off nt
	v_add_co_u32_e32 v4, vcc, s97, v2
	s_addc_u32 s17, s10, s17
	s_nop 0
	v_addc_co_u32_e32 v5, vcc, 0, v3, vcc
	global_load_dwordx4 v[38:41], v[4:5], off nt
	v_add_co_u32_e32 v4, vcc, s30, v2
	s_lshl_b64 s[0:1], s[0:1], 1
	s_nop 0
	v_addc_co_u32_e32 v5, vcc, 0, v3, vcc
	global_load_dwordx4 v[34:37], v[4:5], off nt
	v_add_co_u32_e32 v4, vcc, s83, v2
	s_add_u32 s0, s23, s0
	s_nop 0
	v_addc_co_u32_e32 v5, vcc, 0, v3, vcc
	global_load_dwordx4 v[30:33], v[4:5], off nt
	v_add_co_u32_e32 v4, vcc, s27, v2
	s_addc_u32 s1, s17, s1
	s_nop 0
	v_addc_co_u32_e32 v5, vcc, 0, v3, vcc
	global_load_dwordx4 v[26:29], v[4:5], off nt
	v_add_co_u32_e32 v4, vcc, s28, v2
	v_mov_b32_e32 v65, v1
	s_nop 0
	v_addc_co_u32_e32 v5, vcc, 0, v3, vcc
	global_load_dwordx4 v[22:25], v[4:5], off nt
	v_add_co_u32_e32 v4, vcc, s36, v2
	v_mov_b32_e32 v67, v1
	s_nop 0
	v_addc_co_u32_e32 v5, vcc, 0, v3, vcc
	global_load_dwordx4 v[18:21], v[4:5], off nt
	v_add_co_u32_e32 v4, vcc, s37, v2
	v_mov_b32_e32 v69, v1
	s_nop 0
	v_addc_co_u32_e32 v5, vcc, 0, v3, vcc
	global_load_dwordx4 v[14:17], v[4:5], off nt
	v_add_co_u32_e32 v4, vcc, s64, v2
	v_mov_b32_e32 v71, v1
	s_nop 0
	v_addc_co_u32_e32 v5, vcc, 0, v3, vcc
	global_load_dwordx4 v[10:13], v[4:5], off nt
	v_add_co_u32_e32 v4, vcc, s65, v2
	v_mov_b32_e32 v73, v1
	s_nop 0
	v_addc_co_u32_e32 v5, vcc, 0, v3, vcc
	global_load_dwordx4 v[6:9], v[4:5], off nt
	v_add_co_u32_e32 v2, vcc, s66, v2
	v_mov_b32_e32 v75, v1
	s_nop 0
	v_addc_co_u32_e32 v3, vcc, 0, v3, vcc
	global_load_dwordx4 v[2:5], v[2:3], off nt
	s_waitcnt vmcnt(15)
	ds_write2_b32 v78, v80, v81 offset1:1
	ds_write2_b32 v78, v82, v83 offset0:2 offset1:3
	s_waitcnt vmcnt(14)
	ds_write2_b32 v63, v58, v59 offset1:1
	v_add_u32_e32 v58, 0x418, v78
	ds_write2_b32 v58, v60, v61 offset1:1
	v_add_u32_e32 v58, 0x820, v78
	s_waitcnt vmcnt(13)
	ds_write2_b32 v58, v54, v55 offset1:1
	v_add_u32_e32 v54, 0x828, v78
	ds_write2_b32 v54, v56, v57 offset1:1
	v_add_u32_e32 v54, 0xc30, v78
	s_waitcnt vmcnt(12)
	ds_write2_b32 v54, v50, v51 offset1:1
	v_add_u32_e32 v50, 0xc38, v78
	ds_write2_b32 v50, v52, v53 offset1:1
	v_add_u32_e32 v50, 0x1040, v78
	s_waitcnt vmcnt(11)
	ds_write2_b32 v50, v46, v47 offset1:1
	v_add_u32_e32 v46, 0x1048, v78
	ds_write2_b32 v46, v48, v49 offset1:1
	v_add_u32_e32 v46, 0x1450, v78
	s_add_i32 s13, s13, s18
	s_add_i32 s11, s11, s12
	s_waitcnt vmcnt(10)
	ds_write2_b32 v46, v42, v43 offset1:1
	v_add_u32_e32 v42, 0x1458, v78
	ds_write2_b32 v42, v44, v45 offset1:1
	v_add_u32_e32 v42, 0x1860, v78
	s_cmpk_lt_i32 s13, 0xac0
	s_waitcnt vmcnt(9)
; #define LAS __attribute__((address_space(3)))
; __device__ __forceinline__ void p0_item(const float* s0, const float* s1, int nv0, int nv1, int N, bf16* dst, int K, LAS float* scr, int lane, const float* gain  ) {
;     ...
;     for (int i = 0; i < 16; ++i) { const float gk = gain ? gain[4 * i + r] : 1.f; LAS float* d = scr + (4 * i + r) * 65 + 4 * c4; d[0] = v[i].x * gk; d[1] = v[i].y * gk; d[2] = v[i].z * gk; d[3] = v[i].w * gk; }
;     const int c = lane & 7;
; #pragma unroll
;     for (int j = 0; j < 8; ++j) {
;         const int n = (lane >> 3) + 8 * j; const LAS float* s = scr + (8 * c) * 65 + n;
;         u32x4 o; o.x = cvtpk(s[0 * 65], s[1 * 65]); o.y = cvtpk(s[2 * 65], s[3 * 65]); o.z = cvtpk(s[4 * 65], s[5 * 65]); o.w = cvtpk(s[6 * 65], s[7 * 65]);
;         __builtin_nontemporal_store(o, (u32x4*)(dst + (size_t)n * K + 8 * c));
;     }
	ds_write2_b32 v42, v38, v39 offset1:1
	v_add_u32_e32 v38, 0x1868, v78
	ds_write2_b32 v38, v40, v41 offset1:1
	v_add_u32_e32 v38, 0x1c70, v78
	s_waitcnt vmcnt(8)
	ds_write2_b32 v38, v34, v35 offset1:1
	v_add_u32_e32 v34, 0x1c78, v78
	ds_write2_b32 v34, v36, v37 offset1:1
	v_add_u32_e32 v34, 0x2080, v78
	s_waitcnt vmcnt(7)
	ds_write2_b32 v34, v30, v31 offset1:1
	v_add_u32_e32 v30, 0x2088, v78
	ds_write2_b32 v30, v32, v33 offset1:1
	v_add_u32_e32 v30, 0x2490, v78
	s_waitcnt vmcnt(6)
	ds_write2_b32 v30, v26, v27 offset1:1
	v_add_u32_e32 v26, 0x2498, v78
	ds_write2_b32 v26, v28, v29 offset1:1
	v_add_u32_e32 v26, 0x28a0, v78
	v_add_u32_e32 v28, 0x400, v76
	s_waitcnt vmcnt(5)
	ds_write2_b32 v26, v22, v23 offset1:1
	v_add_u32_e32 v22, 0x28a8, v78
	ds_write2_b32 v22, v24, v25 offset1:1
	v_add_u32_e32 v22, 0x2cb0, v78
	s_waitcnt vmcnt(4)
	ds_write2_b32 v22, v18, v19 offset1:1
	v_add_u32_e32 v18, 0x2cb8, v78
	ds_write2_b32 v18, v20, v21 offset1:1
	v_add_u32_e32 v18, 0x30c0, v78
	s_waitcnt vmcnt(3)
	ds_write2_b32 v18, v14, v15 offset1:1
	v_add_u32_e32 v14, 0x30c8, v78
	ds_write2_b32 v14, v16, v17 offset1:1
	v_add_u32_e32 v14, 0x34d0, v78
	s_waitcnt vmcnt(2)
	ds_write2_b32 v14, v10, v11 offset1:1
	v_add_u32_e32 v10, 0x34d8, v78
	ds_write2_b32 v10, v12, v13 offset1:1
	v_add_u32_e32 v10, 0x38e0, v78
	s_waitcnt vmcnt(1)
	ds_write2_b32 v10, v6, v7 offset1:1
	v_add_u32_e32 v6, 0x38e8, v78
	ds_write2_b32 v6, v8, v9 offset1:1
	v_add_u32_e32 v6, 0x3cf0, v78
	s_waitcnt vmcnt(0)
	ds_write2_b32 v6, v2, v3 offset1:1
	v_add_u32_e32 v2, 0x3cf8, v78
	ds_write2_b32 v2, v4, v5 offset1:1
	ds_read2_b32 v[8:9], v76 offset0:65 offset1:73
	ds_read2_b32 v[10:11], v76 offset1:8
	ds_read2_b32 v[12:13], v76 offset0:130 offset1:138
	ds_read2_b32 v[14:15], v76 offset0:195 offset1:203
	ds_read2_b32 v[16:17], v28 offset0:4 offset1:12
	ds_read2_b32 v[18:19], v28 offset0:69 offset1:77
	ds_read2_b32 v[20:21], v28 offset0:134 offset1:142
	ds_read2_b32 v[22:23], v28 offset0:199 offset1:207
	v_lshl_add_u64 v[2:3], s[0:1], 0, v[64:65]
	v_lshl_add_u64 v[24:25], v[2:3], 0, v[66:67]
	s_waitcnt lgkmcnt(6)
	v_cvt_pk_bf16_f32 v4, v10, v8
	s_waitcnt lgkmcnt(4)
	v_cvt_pk_bf16_f32 v5, v12, v14
	s_waitcnt lgkmcnt(2)
	v_cvt_pk_bf16_f32 v6, v16, v18
	s_waitcnt lgkmcnt(0)
	v_cvt_pk_bf16_f32 v7, v20, v22
	v_add_co_u32_e32 v8, vcc, s25, v24
	global_store_dwordx4 v[24:25], v[4:7], off nt
	s_nop 1
	v_cvt_pk_bf16_f32 v4, v11, v9
	v_cvt_pk_bf16_f32 v5, v13, v15
	v_cvt_pk_bf16_f32 v6, v17, v19
	v_cvt_pk_bf16_f32 v7, v21, v23
	v_addc_co_u32_e32 v9, vcc, 0, v25, vcc
	global_store_dwordx4 v[8:9], v[4:7], off offset:2048 nt
	ds_read2_b32 v[8:9], v76 offset0:16 offset1:24
	ds_read2_b32 v[10:11], v76 offset0:81 offset1:89
	ds_read2_b32 v[12:13], v76 offset0:146 offset1:154
	ds_read2_b32 v[14:15], v76 offset0:211 offset1:219
	ds_read2_b32 v[16:17], v28 offset0:20 offset1:28
	ds_read2_b32 v[18:19], v28 offset0:85 offset1:93
	ds_read2_b32 v[20:21], v28 offset0:150 offset1:158
	ds_read2_b32 v[22:23], v28 offset0:215 offset1:223
	v_add_co_u32_e32 v26, vcc, s26, v24
	s_waitcnt lgkmcnt(6)
	v_cvt_pk_bf16_f32 v4, v8, v10
	v_addc_co_u32_e32 v27, vcc, 0, v25, vcc
	s_waitcnt lgkmcnt(4)
	v_cvt_pk_bf16_f32 v5, v12, v14
	s_waitcnt lgkmcnt(2)
	v_cvt_pk_bf16_f32 v6, v16, v18
	s_waitcnt lgkmcnt(0)
	v_cvt_pk_bf16_f32 v7, v20, v22
	v_add_co_u32_e32 v8, vcc, s83, v24
	global_store_dwordx4 v[26:27], v[4:7], off nt
	s_nop 1
	v_cvt_pk_bf16_f32 v4, v9, v11
	v_cvt_pk_bf16_f32 v5, v13, v15
	v_cvt_pk_bf16_f32 v6, v17, v19
	v_cvt_pk_bf16_f32 v7, v21, v23
	v_addc_co_u32_e32 v9, vcc, 0, v25, vcc
	global_store_dwordx4 v[8:9], v[4:7], off offset:2048 nt
	ds_read2_b32 v[8:9], v76 offset0:32 offset1:40
	ds_read2_b32 v[10:11], v76 offset0:97 offset1:105
	ds_read2_b32 v[12:13], v76 offset0:162 offset1:170
	ds_read2_b32 v[14:15], v76 offset0:227 offset1:235
	ds_read2_b32 v[16:17], v28 offset0:36 offset1:44
	ds_read2_b32 v[18:19], v28 offset0:101 offset1:109
	ds_read2_b32 v[20:21], v28 offset0:166 offset1:174
	ds_read2_b32 v[22:23], v28 offset0:231 offset1:239
	v_lshl_add_u64 v[24:25], v[2:3], 0, v[68:69]
	s_waitcnt lgkmcnt(6)
	v_cvt_pk_bf16_f32 v4, v8, v10
	s_waitcnt lgkmcnt(4)
	v_cvt_pk_bf16_f32 v5, v12, v14
	s_waitcnt lgkmcnt(2)
	v_cvt_pk_bf16_f32 v6, v16, v18
	s_waitcnt lgkmcnt(0)
	v_cvt_pk_bf16_f32 v7, v20, v22
	global_store_dwordx4 v[24:25], v[4:7], off nt
	v_lshl_add_u64 v[24:25], v[2:3], 0, v[72:73]
	s_nop 0
	v_cvt_pk_bf16_f32 v4, v9, v11
	v_cvt_pk_bf16_f32 v5, v13, v15
	v_cvt_pk_bf16_f32 v6, v17, v19
	v_cvt_pk_bf16_f32 v7, v21, v23
	v_lshl_add_u64 v[8:9], v[2:3], 0, v[70:71]
	global_store_dwordx4 v[8:9], v[4:7], off nt
	ds_read2_b32 v[8:9], v76 offset0:48 offset1:56
	ds_read2_b32 v[10:11], v76 offset0:113 offset1:121
	ds_read2_b32 v[12:13], v76 offset0:178 offset1:186
	ds_read2_b32 v[14:15], v76 offset0:243 offset1:251
	ds_read2_b32 v[16:17], v28 offset0:52 offset1:60
	ds_read2_b32 v[18:19], v28 offset0:117 offset1:125
	ds_read2_b32 v[20:21], v28 offset0:182 offset1:190
	ds_read2_b32 v[22:23], v28 offset0:247 offset1:255
	v_lshl_add_u64 v[2:3], v[2:3], 0, v[74:75]
	s_waitcnt lgkmcnt(6)
	v_cvt_pk_bf16_f32 v4, v8, v10
	s_waitcnt lgkmcnt(4)
	v_cvt_pk_bf16_f32 v5, v12, v14
	s_waitcnt lgkmcnt(2)
	v_cvt_pk_bf16_f32 v6, v16, v18
	s_waitcnt lgkmcnt(0)
	v_cvt_pk_bf16_f32 v7, v20, v22
	global_store_dwordx4 v[24:25], v[4:7], off nt
	s_nop 1
	v_cvt_pk_bf16_f32 v4, v9, v11
	v_cvt_pk_bf16_f32 v5, v13, v15
	v_cvt_pk_bf16_f32 v6, v17, v19
	v_cvt_pk_bf16_f32 v7, v21, v23
	global_store_dwordx4 v[2:3], v[4:7], off nt
	s_cbranch_scc1 .LBB0_1605

; #define LAS __attribute__((address_space(3)))
; __device__ __forceinline__ LAS unsigned char* lds_base() { extern __shared__ __attribute__((aligned(16))) unsigned char lds_any_[]; return (LAS unsigned char*)lds_any_; }
; #define OPQ_V(x) asm volatile("" : "+v"(x))
; #define OPQ_P(x) do { unsigned long long t_ = (unsigned long long)(x); asm volatile("" : "+s"(t_)); x = (decltype(x))(GASP unsigned char*)t_; } while (0)
; __global__ void __launch_bounds__(512, 2) fwd_megakernel(Args args) {
;     ...
;         {
;             unsigned tmask = 0u; int tl = l;
;             if (k == 0) tmask = l == 0 ? (CV_SMALL | CV_D2) : (CV_SMALL | CV_WIN);
;             else if (k == 2) tmask = CV_GU2;
;             else if (k == 7) { if (l == 0) { tl = 1; tmask = CV_GU1; } else tmask = CV_D2; }
;             if (tmask) {
;                 const int nleft = ((M / 256) * ((k == 2 ? INP : 2 * FF) / 256)) % G;
;                 if (bx >= nleft) {
;                     __syncthreads();
;                     int tid_ = threadIdx.x; OPQ_V(tid_); const int lane = tid_ & 63, wave = __builtin_amdgcn_readfirstlane(tid_ >> 6);
;                     LAS float* scr = (LAS float*)(lds_base() + wave * 16640);
;                     unsigned char* ws2 = args.ws; OPQ_P(ws2);
;                     conv_set(CV_ARGS(args), ws2, tl, tmask, scr, (bx - nleft) * 8 + wave, (G - nleft) * 8, lane);
;                 }
;             }
.LBB0_1624:
	s_cmp_lg_u32 s89, 2
	s_cbranch_scc1 .Ltail2_done
	v_readlane_b32 s0, v255, 62
	s_nop 3
	s_cmp_lg_u32 s0, 0
	s_cbranch_scc1 .Ltail2_fin
	s_mov_b32 s0, 1
	v_writelane_b32 v255, s0, 62
	v_readlane_b32 s62, v253, 1
	v_readlane_b32 s63, v253, 2
	v_readlane_b32 s34, v255, 19
	v_readlane_b32 s35, v255, 20
	s_mov_b32 s3, 2
	s_mov_b32 s19, 0x80
	s_mov_b32 s20, 1
	s_branch .LBB0_1413
.Ltail2_fin:
	s_mov_b32 s0, 2
	v_writelane_b32 v255, s0, 62
